# P2 finalizes: the 128 gain values are fetched with one 8-byte-per-lane load per wave, parked in a private LDS strip above the tile ring and read back per lane (7 fewer row-scattered loads per finalize
# baseline (speedup 1.0000x reference)
; template <bool DIFF>
; __device__ __forceinline__ void attn_item(LAS unsigned char* lds, const bf16_t* Z, bf16_t* MIX, int b, int h, int t, float lam, float shift, const float* gain, int tid, int wid, int lane) {
;     ...
;     float inv0 = 1.f, inv1 = 0.f;
;     if (DIFF) {
; #pragma unroll
;         for (int c = 0; c < NC; ++c) l[c] = quad_sum(l[c]);
;         inv0 = 1.0f / l[0]; inv1 = lam / l[NC - 1];
;     }
;     float ss = 0.f;
; #pragma unroll
;     for (int eb = 0; eb < 8; ++eb)
; #pragma unroll
;         for (int i = 0; i < 4; ++i) { float v = O[0][eb][i] * inv0; if (DIFF) v -= O[NC - 1][eb][i] * inv1; O[0][eb][i] = v; ss += v * v; }
;     ss = quad_sum(ss);
;     const float r = rsqrtf(ss * (1.0f / 128.0f) + EPS) * (DIFF ? 0.8f : 1.0f);
;     const int row = row0 + q16;
;     const bf16_t* gp = Z + (size_t)row * DIN + gcol + 4 * quad;
;     bf16_t* op = MIX + (size_t)row * DM + (DIFF ? 1024 : 0) + 128 * h + 4 * quad;
; #pragma unroll
;     for (int eb = 0; eb < 8; ++eb) {
;         const u32x2 gw = *(const u32x2*)(gp + 16 * eb);
;         const f32x4 gn = *(const f32x4*)(gain + 16 * eb + 4 * quad);
.Ldx_done:
.LBB0_574:
	s_waitcnt lgkmcnt(0)
	ds_swizzle_b32 v68, v131 offset:swizzle(SWAP,16)
	ds_swizzle_b32 v69, v130 offset:swizzle(SWAP,16)
	v_ashrrev_i32_e32 v129, 31, v128
	v_lshlrev_b64 v[80:81], 1, v[128:129]
	s_lshl_b32 s86, s80, 1
	s_waitcnt lgkmcnt(0)
	v_add_f32_e32 v68, v131, v68
	v_mov_b32_e32 v70, v68
	s_nop 1
	v_permlane32_swap_b32_e32 v68, v70
	v_add_f32_e32 v68, v68, v70
	v_div_scale_f32 v70, s[0:1], v68, v68, 1.0
	v_rcp_f32_e32 v72, v70
	v_add_f32_e32 v69, v130, v69
	v_mov_b32_e32 v71, v69
	s_nop 1
	v_permlane32_swap_b32_e32 v69, v71
	v_add_f32_e32 v69, v69, v71
	v_fma_f32 v71, -v70, v72, 1.0
	v_fmac_f32_e32 v72, v71, v72
	v_div_scale_f32 v71, vcc, 1.0, v68, 1.0
	v_mul_f32_e32 v73, v71, v72
	v_fma_f32 v74, -v70, v73, v71
	v_fmac_f32_e32 v73, v74, v72
	v_fma_f32 v70, -v70, v73, v71
	v_div_scale_f32 v71, s[0:1], v69, v69, s28
	v_rcp_f32_e32 v74, v71
	v_div_fmas_f32 v70, v70, v72, v73
	v_div_fixup_f32 v76, v70, v68, 1.0
	s_movk_i32 s0, 0x3000
	v_fma_f32 v68, -v71, v74, 1.0
	v_fmac_f32_e32 v74, v68, v74
	v_div_scale_f32 v68, vcc, s28, v69, s28
	v_mul_f32_e32 v70, v68, v74
	v_fma_f32 v72, -v71, v70, v68
	v_fmac_f32_e32 v70, v72, v74
	v_fma_f32 v68, -v71, v70, v68
	v_lshl_add_u64 v[72:73], v[126:127], 0, v[80:81]
	v_div_fmas_f32 v68, v68, v74, v70
	v_lshl_add_u64 v[70:71], v[72:73], 0, s[92:93]
	v_add_co_u32_e32 v72, vcc, s0, v72
	v_div_fixup_f32 v78, v68, v69, s28
	v_lshlrev_b64 v[68:69], 12, v[124:125]
	v_addc_co_u32_e32 v73, vcc, 0, v73, vcc
	v_lshl_add_u64 v[82:83], s[88:89], 0, v[68:69]
	v_lshl_add_u64 v[68:69], v[128:129], 2, s[84:85]
	v_mbcnt_lo_u32_b32 v150, -1, 0
	v_mbcnt_hi_u32_b32 v150, -1, v150
	v_and_b32_e32 v150, 16, v150
	v_lshrrev_b32_e32 v151, 1, v150
	v_add_u32_e32 v150, v150, v151
	v_mov_b32_e32 v151, 0
	v_lshl_add_u64 v[152:153], v[70:71], 0, v[150:151]
	v_mbcnt_lo_u32_b32 v154, -1, 0
	v_mbcnt_hi_u32_b32 v154, -1, v154
	v_lshlrev_b32_e32 v155, 3, v154
	v_lshrrev_b32_e32 v156, 4, v154
	v_lshlrev_b32_e32 v156, 4, v156
	v_sub_u32_e32 v158, v155, v156
	v_mov_b32_e32 v159, 0
	v_lshl_add_u64 v[158:159], v[68:69], 0, v[158:159]
	global_load_dwordx2 v[160:161], v[158:159], off
	global_load_dwordx4 v[116:119], v[152:153], off
	global_load_dwordx4 v[120:123], v[152:153], off offset:64
	global_load_dwordx4 v[132:135], v[152:153], off offset:128
	global_load_dwordx4 v[136:139], v[152:153], off offset:192
	v_pk_mul_f32 v[56:57], v[56:57], v[78:79] op_sel_hi:[1,0]
	v_pk_mul_f32 v[58:59], v[58:59], v[78:79] op_sel_hi:[1,0]
	v_pk_fma_f32 v[56:57], v[64:65], v[76:77], v[56:57] op_sel_hi:[1,0,1] neg_lo:[0,0,1] neg_hi:[0,0,1]
	v_pk_fma_f32 v[58:59], v[66:67], v[76:77], v[58:59] op_sel_hi:[1,0,1] neg_lo:[0,0,1] neg_hi:[0,0,1]
	v_pk_mul_f32 v[64:65], v[56:57], v[56:57]
	v_pk_mul_f32 v[66:67], v[58:59], v[58:59]
	v_pk_mul_f32 v[52:53], v[52:53], v[78:79] op_sel_hi:[1,0]
	v_add_f32_e32 v64, v64, v65
	v_pk_fma_f32 v[52:53], v[60:61], v[76:77], v[52:53] op_sel_hi:[1,0,1] neg_lo:[0,0,1] neg_hi:[0,0,1]
	v_add_f32_e32 v64, v66, v64
	v_pk_mul_f32 v[54:55], v[54:55], v[78:79] op_sel_hi:[1,0]
	v_pk_mul_f32 v[60:61], v[52:53], v[52:53]
	v_add_f32_e32 v64, v67, v64
	v_pk_fma_f32 v[54:55], v[62:63], v[76:77], v[54:55] op_sel_hi:[1,0,1] neg_lo:[0,0,1] neg_hi:[0,0,1]
	v_add_f32_e32 v60, v60, v64
	v_pk_mul_f32 v[62:63], v[54:55], v[54:55]
	v_pk_mul_f32 v[44:45], v[44:45], v[78:79] op_sel_hi:[1,0]
	v_add_f32_e32 v60, v61, v60
	v_pk_fma_f32 v[44:45], v[48:49], v[76:77], v[44:45] op_sel_hi:[1,0,1] neg_lo:[0,0,1] neg_hi:[0,0,1]
	v_add_f32_e32 v60, v62, v60
	v_pk_mul_f32 v[46:47], v[46:47], v[78:79] op_sel_hi:[1,0]
	v_pk_mul_f32 v[48:49], v[44:45], v[44:45]
	v_add_f32_e32 v60, v63, v60
	v_pk_fma_f32 v[46:47], v[50:51], v[76:77], v[46:47] op_sel_hi:[1,0,1] neg_lo:[0,0,1] neg_hi:[0,0,1]
	v_add_f32_e32 v48, v48, v60
	v_pk_mul_f32 v[50:51], v[46:47], v[46:47]
	v_pk_mul_f32 v[36:37], v[36:37], v[78:79] op_sel_hi:[1,0]
	v_add_f32_e32 v48, v49, v48
	v_pk_fma_f32 v[36:37], v[40:41], v[76:77], v[36:37] op_sel_hi:[1,0,1] neg_lo:[0,0,1] neg_hi:[0,0,1]
	v_add_f32_e32 v48, v50, v48
	v_pk_mul_f32 v[38:39], v[38:39], v[78:79] op_sel_hi:[1,0]
	v_pk_mul_f32 v[40:41], v[36:37], v[36:37]
	v_add_f32_e32 v48, v51, v48
	v_pk_fma_f32 v[38:39], v[42:43], v[76:77], v[38:39] op_sel_hi:[1,0,1] neg_lo:[0,0,1] neg_hi:[0,0,1]
	v_add_f32_e32 v40, v40, v48
	v_pk_mul_f32 v[42:43], v[38:39], v[38:39]
	v_pk_mul_f32 v[28:29], v[28:29], v[78:79] op_sel_hi:[1,0]
	v_add_f32_e32 v40, v41, v40
	v_pk_fma_f32 v[28:29], v[32:33], v[76:77], v[28:29] op_sel_hi:[1,0,1] neg_lo:[0,0,1] neg_hi:[0,0,1]
	v_add_f32_e32 v40, v42, v40
	v_pk_mul_f32 v[30:31], v[30:31], v[78:79] op_sel_hi:[1,0]
	v_pk_mul_f32 v[32:33], v[28:29], v[28:29]
	v_add_f32_e32 v40, v43, v40
	v_pk_fma_f32 v[30:31], v[34:35], v[76:77], v[30:31] op_sel_hi:[1,0,1] neg_lo:[0,0,1] neg_hi:[0,0,1]
	v_add_f32_e32 v32, v32, v40
	v_pk_mul_f32 v[34:35], v[30:31], v[30:31]
	v_pk_mul_f32 v[20:21], v[20:21], v[78:79] op_sel_hi:[1,0]
	v_add_f32_e32 v32, v33, v32
	v_pk_fma_f32 v[20:21], v[24:25], v[76:77], v[20:21] op_sel_hi:[1,0,1] neg_lo:[0,0,1] neg_hi:[0,0,1]
	v_add_f32_e32 v32, v34, v32
	v_pk_mul_f32 v[22:23], v[22:23], v[78:79] op_sel_hi:[1,0]
	v_pk_mul_f32 v[24:25], v[20:21], v[20:21]
	v_add_f32_e32 v32, v35, v32
	v_pk_fma_f32 v[22:23], v[26:27], v[76:77], v[22:23] op_sel_hi:[1,0,1] neg_lo:[0,0,1] neg_hi:[0,0,1]
	v_add_f32_e32 v24, v24, v32
	v_pk_mul_f32 v[26:27], v[22:23], v[22:23]
	v_pk_mul_f32 v[12:13], v[12:13], v[78:79] op_sel_hi:[1,0]
	v_add_f32_e32 v24, v25, v24
	v_pk_fma_f32 v[12:13], v[16:17], v[76:77], v[12:13] op_sel_hi:[1,0,1] neg_lo:[0,0,1] neg_hi:[0,0,1]
	v_add_f32_e32 v24, v26, v24
	v_pk_mul_f32 v[14:15], v[14:15], v[78:79] op_sel_hi:[1,0]
	v_pk_mul_f32 v[16:17], v[12:13], v[12:13]
	v_add_f32_e32 v24, v27, v24
	v_pk_fma_f32 v[14:15], v[18:19], v[76:77], v[14:15] op_sel_hi:[1,0,1] neg_lo:[0,0,1] neg_hi:[0,0,1]
	v_add_f32_e32 v16, v16, v24
	v_pk_mul_f32 v[18:19], v[14:15], v[14:15]
	v_pk_mul_f32 v[4:5], v[4:5], v[78:79] op_sel_hi:[1,0]
	v_add_f32_e32 v16, v17, v16
	v_pk_fma_f32 v[8:9], v[8:9], v[76:77], v[4:5] op_sel_hi:[1,0,1] neg_lo:[0,0,1] neg_hi:[0,0,1]
	v_add_f32_e32 v16, v18, v16
	v_pk_mul_f32 v[6:7], v[6:7], v[78:79] op_sel_hi:[1,0]
	v_pk_mul_f32 v[4:5], v[8:9], v[8:9]
	v_add_f32_e32 v16, v19, v16
	v_pk_fma_f32 v[10:11], v[10:11], v[76:77], v[6:7] op_sel_hi:[1,0,1] neg_lo:[0,0,1] neg_hi:[0,0,1]
	v_add_f32_e32 v4, v4, v16
	v_pk_mul_f32 v[6:7], v[10:11], v[10:11]
	v_add_f32_e32 v4, v5, v4
	v_add_f32_e32 v4, v6, v4
	v_add_f32_e32 v6, v7, v4
	ds_swizzle_b32 v7, v6 offset:swizzle(SWAP,16)
	v_mov_b32_e32 v18, 0x358637bd
	s_mov_b32 s87, s27
	v_lshl_add_u64 v[4:5], v[82:83], 0, s[86:87]
	v_lshl_add_u64 v[16:17], v[4:5], 0, v[80:81]
	s_waitcnt lgkmcnt(0)
; __device__ __forceinline__ unsigned cvtpk(float lo, float hi) { f32x2 v = {lo, hi}; bf16x2_t b = __builtin_convertvector(v, bf16x2_t); return __builtin_bit_cast(unsigned, b); }
; __device__ __forceinline__ float bflo(unsigned u) { return __uint_as_float(u << 16); }
; __device__ __forceinline__ float bfhi(unsigned u) { return __uint_as_float(u & 0xffff0000u); }
; template <bool DIFF>
; __device__ __forceinline__ void attn_item(LAS unsigned char* lds, const bf16_t* Z, bf16_t* MIX, int b, int h, int t, float lam, float shift, const float* gain, int tid, int wid, int lane) {
;     ...
;     const float r = rsqrtf(ss * (1.0f / 128.0f) + EPS) * (DIFF ? 0.8f : 1.0f);
;     const int row = row0 + q16;
;     const bf16_t* gp = Z + (size_t)row * DIN + gcol + 4 * quad;
;     bf16_t* op = MIX + (size_t)row * DM + (DIFF ? 1024 : 0) + 128 * h + 4 * quad;
; #pragma unroll
;     for (int eb = 0; eb < 8; ++eb) {
;         const u32x2 gw = *(const u32x2*)(gp + 16 * eb);
;         const f32x4 gn = *(const f32x4*)(gain + 16 * eb + 4 * quad);
;         u32x2 w; w.x = cvtpk(O[0][eb][0] * r * gn.x * bflo(gw.x), O[0][eb][1] * r * gn.y * bfhi(gw.x));
;         w.y = cvtpk(O[0][eb][2] * r * gn.z * bflo(gw.y), O[0][eb][3] * r * gn.w * bfhi(gw.y));
;         *(u32x2*)(op + 16 * eb) = w;
	v_add_f32_e32 v6, v6, v7
	v_mov_b32_e32 v7, v6
	s_nop 1
	v_permlane32_swap_b32_e32 v6, v7
	v_add_f32_e32 v6, v6, v7
	v_fmamk_f32 v6, v6, 0x3c000000, v18
	v_mul_f32_e32 v7, 0x4b800000, v6
	v_cmp_gt_f32_e32 vcc, s42, v6
	s_nop 1
	v_cndmask_b32_e32 v6, v6, v7, vcc
	v_rsq_f32_e32 v24, v6
	s_nop 0
	v_mul_f32_e32 v25, 0x45800000, v24
	v_cndmask_b32_e32 v24, v24, v25, vcc
	v_mul_f32_e32 v24, 0x3f4ccccd, v24
	s_waitcnt vmcnt(0)
	s_lshr_b32 s22, s90, 1
	s_add_i32 s22, s22, 0x20000
	v_add_u32_e32 v155, s22, v155
	ds_write_b64 v155, v[160:161]
	v_add_u32_e32 v156, s22, v156
	ds_read_b128 v[84:87], v156
	ds_read_b128 v[88:91], v156 offset:64
	ds_read_b128 v[92:95], v156 offset:128
	ds_read_b128 v[96:99], v156 offset:192
	ds_read_b128 v[100:103], v156 offset:256
	ds_read_b128 v[104:107], v156 offset:320
	ds_read_b128 v[108:111], v156 offset:384
	ds_read_b128 v[112:115], v156 offset:448
	v_permlane16_swap_b32_e32 v116, v118
	v_permlane16_swap_b32_e32 v117, v119
	v_permlane16_swap_b32_e32 v120, v122
	v_permlane16_swap_b32_e32 v121, v123
	v_permlane16_swap_b32_e32 v132, v134
	v_permlane16_swap_b32_e32 v133, v135
	v_permlane16_swap_b32_e32 v136, v138
	v_permlane16_swap_b32_e32 v137, v139
	s_waitcnt lgkmcnt(0)
	v_mbcnt_lo_u32_b32 v150, -1, 0
	v_mbcnt_hi_u32_b32 v150, -1, v150
	v_and_b32_e32 v150, 16, v150
	v_lshrrev_b32_e32 v151, 1, v150
	v_add_u32_e32 v150, v150, v151
	v_mov_b32_e32 v151, 0
	v_lshl_add_u64 v[148:149], v[16:17], 0, v[150:151]
	v_pk_mul_f32 v[56:57], v[56:57], v[24:25] op_sel_hi:[1,0]
	v_pk_mul_f32 v[58:59], v[58:59], v[24:25] op_sel_hi:[1,0]
	v_lshlrev_b32_e32 v60, 16, v116
	v_and_b32_e32 v61, 0xffff0000, v116
	v_lshlrev_b32_e32 v62, 16, v117
	v_and_b32_e32 v63, 0xffff0000, v117
	v_pk_mul_f32 v[56:57], v[84:85], v[56:57]
	v_pk_mul_f32 v[58:59], v[86:87], v[58:59]
	v_pk_mul_f32 v[56:57], v[56:57], v[60:61]
	v_pk_mul_f32 v[58:59], v[58:59], v[62:63]
	v_cvt_pk_bf16_f32 v56, v56, v57
	v_cvt_pk_bf16_f32 v57, v58, v59
	v_pk_mul_f32 v[52:53], v[52:53], v[24:25] op_sel_hi:[1,0]
	v_pk_mul_f32 v[54:55], v[54:55], v[24:25] op_sel_hi:[1,0]
	v_lshlrev_b32_e32 v40, 16, v118
	v_and_b32_e32 v41, 0xffff0000, v118
	v_lshlrev_b32_e32 v42, 16, v119
	v_and_b32_e32 v43, 0xffff0000, v119
	v_pk_mul_f32 v[52:53], v[88:89], v[52:53]
	v_pk_mul_f32 v[54:55], v[90:91], v[54:55]
	v_pk_mul_f32 v[52:53], v[52:53], v[40:41]
	v_pk_mul_f32 v[54:55], v[54:55], v[42:43]
	v_cvt_pk_bf16_f32 v58, v52, v53
	v_cvt_pk_bf16_f32 v59, v54, v55
	s_nop 1
	v_permlane16_swap_b32_e32 v56, v58
	v_permlane16_swap_b32_e32 v57, v59
	global_store_dwordx4 v[148:149], v[56:59], off offset:2048
	v_pk_mul_f32 v[44:45], v[44:45], v[24:25] op_sel_hi:[1,0]
	v_pk_mul_f32 v[46:47], v[46:47], v[24:25] op_sel_hi:[1,0]
	v_lshlrev_b32_e32 v60, 16, v120
	v_and_b32_e32 v61, 0xffff0000, v120
	v_lshlrev_b32_e32 v62, 16, v121
	v_and_b32_e32 v63, 0xffff0000, v121
	v_pk_mul_f32 v[44:45], v[92:93], v[44:45]
	v_pk_mul_f32 v[46:47], v[94:95], v[46:47]
	v_pk_mul_f32 v[44:45], v[44:45], v[60:61]
	v_pk_mul_f32 v[46:47], v[46:47], v[62:63]
	v_cvt_pk_bf16_f32 v44, v44, v45
	v_cvt_pk_bf16_f32 v45, v46, v47
	v_pk_mul_f32 v[36:37], v[36:37], v[24:25] op_sel_hi:[1,0]
	v_pk_mul_f32 v[38:39], v[38:39], v[24:25] op_sel_hi:[1,0]
	v_lshlrev_b32_e32 v40, 16, v122
	v_and_b32_e32 v41, 0xffff0000, v122
	v_lshlrev_b32_e32 v42, 16, v123
	v_and_b32_e32 v43, 0xffff0000, v123
	v_pk_mul_f32 v[36:37], v[96:97], v[36:37]
	v_pk_mul_f32 v[38:39], v[98:99], v[38:39]
	v_pk_mul_f32 v[36:37], v[36:37], v[40:41]
	v_pk_mul_f32 v[38:39], v[38:39], v[42:43]
	v_cvt_pk_bf16_f32 v46, v36, v37
	v_cvt_pk_bf16_f32 v47, v38, v39
	s_nop 1
	v_permlane16_swap_b32_e32 v44, v46
	v_permlane16_swap_b32_e32 v45, v47
	global_store_dwordx4 v[148:149], v[44:47], off offset:2112
	v_pk_mul_f32 v[28:29], v[28:29], v[24:25] op_sel_hi:[1,0]
	v_pk_mul_f32 v[30:31], v[30:31], v[24:25] op_sel_hi:[1,0]
	v_lshlrev_b32_e32 v60, 16, v132
	v_and_b32_e32 v61, 0xffff0000, v132
	v_lshlrev_b32_e32 v62, 16, v133
	v_and_b32_e32 v63, 0xffff0000, v133
	v_pk_mul_f32 v[28:29], v[100:101], v[28:29]
	v_pk_mul_f32 v[30:31], v[102:103], v[30:31]
	v_pk_mul_f32 v[28:29], v[28:29], v[60:61]
	v_pk_mul_f32 v[30:31], v[30:31], v[62:63]
	v_cvt_pk_bf16_f32 v28, v28, v29
	v_cvt_pk_bf16_f32 v29, v30, v31
	v_pk_mul_f32 v[20:21], v[20:21], v[24:25] op_sel_hi:[1,0]
	v_pk_mul_f32 v[22:23], v[22:23], v[24:25] op_sel_hi:[1,0]
	v_lshlrev_b32_e32 v40, 16, v134
	v_and_b32_e32 v41, 0xffff0000, v134
	v_lshlrev_b32_e32 v42, 16, v135
	v_and_b32_e32 v43, 0xffff0000, v135
	v_pk_mul_f32 v[20:21], v[104:105], v[20:21]
	v_pk_mul_f32 v[22:23], v[106:107], v[22:23]
	v_pk_mul_f32 v[20:21], v[20:21], v[40:41]
	v_pk_mul_f32 v[22:23], v[22:23], v[42:43]
	v_cvt_pk_bf16_f32 v30, v20, v21
	v_cvt_pk_bf16_f32 v31, v22, v23
	s_nop 1
	v_permlane16_swap_b32_e32 v28, v30
	v_permlane16_swap_b32_e32 v29, v31
	global_store_dwordx4 v[148:149], v[28:31], off offset:2176
	v_pk_mul_f32 v[12:13], v[12:13], v[24:25] op_sel_hi:[1,0]
	v_pk_mul_f32 v[14:15], v[14:15], v[24:25] op_sel_hi:[1,0]
	v_lshlrev_b32_e32 v60, 16, v136
	v_and_b32_e32 v61, 0xffff0000, v136
	v_lshlrev_b32_e32 v62, 16, v137
	v_and_b32_e32 v63, 0xffff0000, v137
	v_pk_mul_f32 v[12:13], v[108:109], v[12:13]
	v_pk_mul_f32 v[14:15], v[110:111], v[14:15]
	v_pk_mul_f32 v[12:13], v[12:13], v[60:61]
	v_pk_mul_f32 v[14:15], v[14:15], v[62:63]
	v_cvt_pk_bf16_f32 v12, v12, v13
	v_cvt_pk_bf16_f32 v13, v14, v15
	v_pk_mul_f32 v[8:9], v[8:9], v[24:25] op_sel_hi:[1,0]
	v_pk_mul_f32 v[10:11], v[10:11], v[24:25] op_sel_hi:[1,0]
	v_lshlrev_b32_e32 v40, 16, v138
	v_and_b32_e32 v41, 0xffff0000, v138
	v_lshlrev_b32_e32 v42, 16, v139
	v_and_b32_e32 v43, 0xffff0000, v139
	v_pk_mul_f32 v[8:9], v[112:113], v[8:9]
	v_pk_mul_f32 v[10:11], v[114:115], v[10:11]
	v_pk_mul_f32 v[8:9], v[8:9], v[40:41]
	v_pk_mul_f32 v[10:11], v[10:11], v[42:43]
	v_cvt_pk_bf16_f32 v14, v8, v9
	v_cvt_pk_bf16_f32 v15, v10, v11
	s_nop 1
	v_permlane16_swap_b32_e32 v12, v14
	v_permlane16_swap_b32_e32 v13, v15
	global_store_dwordx4 v[148:149], v[12:15], off offset:2240
	s_nop 1
	v_mov_b32_e32 v15, v183
	s_cmp_lg_u32 s98, 0
	s_cbranch_scc1 .Lp2_item_done
	s_cmp_lt_i32 s9, 3
	s_cbranch_scc1 .LBB0_579
	s_cmp_lt_i32 s9, 4
	s_cbranch_scc1 .LBB0_580
	s_cmp_lt_i32 s9, 5
	s_cbranch_scc1 .LBB0_581
	s_cmp_lg_u32 s9, 5
	s_cbranch_scc0 .LBB0_582
	s_cmp_eq_u32 s9, 6
	s_cselect_b64 vcc, -1, 0
	v_mov_b32_e32 v4, 0xba38b001
	v_mov_b32_e32 v5, 0xbab8b5c7
	v_cndmask_b32_e32 v12, v4, v5, vcc
	s_cbranch_execz .LBB0_583
	s_branch .LBB0_584

; __device__ __forceinline__ int lane_id() { return (int)__builtin_amdgcn_mbcnt_hi(~0u, __builtin_amdgcn_mbcnt_lo(~0u, 0u)); }
; __device__ __forceinline__ void ret_pair(LAS unsigned char* lds, const bf16_t* Z, bf16_t* MIX, int b, int h, int tA, int tB, const float* gain, int wid) {
;     ...
;     int lf = lane_id(); asm volatile("" : "+v"(lf)); const int q16f = lf & 15, quadf = (lf >> 4) & 3;
; #pragma unroll
;     for (int which = 0; which < 2; ++which) {
;         f32x4 (&O)[8] = which ? OB : OA;
;         float ss = 0.f;
; #pragma unroll
;         for (int eb = 0; eb < 8; ++eb)
; #pragma unroll
;             for (int i = 0; i < 4; ++i) ss += O[eb][i] * O[eb][i];
;         ss = quad_sum(ss);
;         const float r = rsqrtf(ss * (1.0f / 128.0f) + EPS);
;         const int row = (which ? rowB0 : rowA0) + q16f;
;         const bf16_t* gp = Z + (size_t)row * DIN + gcol + 4 * quadf;
;         bf16_t* op = MIX + (size_t)row * DM + 128 * h + 4 * quadf;
.LBB0_640:
	s_lshl_b32 s0, s80, 2
	v_readlane_b32 s1, v254, 24
	s_add_u32 s0, s1, s0
	v_readlane_b32 s1, v254, 23
	v_readlane_b32 s2, v255, 3
	s_waitcnt lgkmcnt(0)
	v_mov_b32_e32 v4, v183
	s_addc_u32 s1, s1, 0
	s_add_i32 s4, s2, 1
	s_add_u32 s2, s30, s86
	v_and_b32_e32 v93, 15, v4
	v_lshrrev_b32_e32 v4, 2, v4
	s_addc_u32 s3, s31, 0
	v_and_b32_e32 v4, 12, v4
	v_lshlrev_b32_e32 v180, 1, v4
	v_lshlrev_b32_e32 v4, 2, v4
	v_mov_b32_e32 v5, v181
	v_or_b32_e32 v32, s5, v93
	v_mov_b64_e32 v[6:7], s[2:3]
	v_lshl_add_u64 v[4:5], s[0:1], 0, v[4:5]
	v_readlane_b32 s3, v255, 7
	s_mov_b64 s[6:7], 0x1000
	v_mad_i64_i32 v[8:9], vcc, v32, s36, v[6:7]
	v_mov_b32_e32 v29, v181
	v_or_b32_e32 v30, s3, v93
	v_lshl_add_u64 v[10:11], v[8:9], 0, v[180:181]
	v_mad_i64_i32 v[6:7], vcc, v30, s36, v[6:7]
	v_lshl_add_u64 v[10:11], v[10:11], 0, s[6:7]
	v_lshl_add_u64 v[6:7], v[6:7], 0, v[180:181]
	s_add_u32 s0, s88, s86
	s_addc_u32 s1, s89, 0
	v_lshl_add_u64 v[6:7], v[6:7], 0, s[6:7]
	v_mbcnt_lo_u32_b32 v178, -1, 0
	v_mbcnt_hi_u32_b32 v178, -1, v178
	v_and_b32_e32 v178, 16, v178
	v_lshrrev_b32_e32 v179, 1, v178
	v_add_u32_e32 v178, v178, v179
	v_mov_b32_e32 v179, 0
	v_lshl_add_u64 v[170:171], v[10:11], 0, v[178:179]
	v_lshl_add_u64 v[172:173], v[6:7], 0, v[178:179]
	v_mbcnt_lo_u32_b32 v128, -1, 0
	v_mbcnt_hi_u32_b32 v128, -1, v128
	v_lshlrev_b32_e32 v129, 3, v128
	v_lshrrev_b32_e32 v128, 4, v128
	v_lshlrev_b32_e32 v128, 4, v128
	v_sub_u32_e32 v130, v129, v128
	v_mov_b32_e32 v131, 0
	v_lshl_add_u64 v[130:131], v[4:5], 0, v[130:131]
	global_load_dwordx2 v[132:133], v[130:131], off
	s_lshr_b32 s6, s90, 1
	s_add_i32 s6, s6, 0x20000
	v_add_u32_e32 v129, s6, v129
	v_add_u32_e32 v128, s6, v128
	global_load_dwordx4 v[134:137], v[170:171], off
	global_load_dwordx4 v[150:153], v[172:173], off
	global_load_dwordx4 v[138:141], v[170:171], off offset:64
	global_load_dwordx4 v[154:157], v[172:173], off offset:64
	global_load_dwordx4 v[142:145], v[170:171], off offset:128
	global_load_dwordx4 v[158:161], v[172:173], off offset:128
	global_load_dwordx4 v[146:149], v[170:171], off offset:192
	global_load_dwordx4 v[162:165], v[172:173], off offset:192
	v_lshl_add_u64 v[8:9], s[0:1], 0, v[180:181]
	v_mov_b32_e32 v28, v32
	v_mov_b32_e32 v31, v181
	v_lshlrev_b64 v[28:29], 12, v[28:29]
	v_lshlrev_b64 v[30:31], 12, v[30:31]
	v_lshl_add_u64 v[166:167], v[8:9], 0, v[28:29]
	v_lshl_add_u64 v[168:169], v[8:9], 0, v[30:31]
	v_mul_f32_e32 v33, v81, v81
	v_fmac_f32_e32 v33, v80, v80
	v_fmac_f32_e32 v33, v82, v82
	v_fmac_f32_e32 v33, v83, v83
	v_fmac_f32_e32 v33, v76, v76
	v_fmac_f32_e32 v33, v77, v77
	v_fmac_f32_e32 v33, v78, v78
	v_fmac_f32_e32 v33, v79, v79
	v_fmac_f32_e32 v33, v72, v72
	v_fmac_f32_e32 v33, v73, v73
	v_fmac_f32_e32 v33, v74, v74
	v_fmac_f32_e32 v33, v75, v75
	v_fmac_f32_e32 v33, v68, v68
	v_fmac_f32_e32 v33, v69, v69
	v_fmac_f32_e32 v33, v70, v70
	v_fmac_f32_e32 v33, v71, v71
	v_fmac_f32_e32 v33, v64, v64
	v_fmac_f32_e32 v33, v65, v65
	v_fmac_f32_e32 v33, v66, v66
	v_fmac_f32_e32 v33, v67, v67
	v_fmac_f32_e32 v33, v60, v60
	v_fmac_f32_e32 v33, v61, v61
	v_fmac_f32_e32 v33, v62, v62
	v_fmac_f32_e32 v33, v63, v63
	v_pk_mul_f32 v[84:85], v[56:57], v[56:57]
	v_pk_mul_f32 v[8:9], v[58:59], v[58:59]
	v_add_f32_e32 v33, v84, v33
	v_add_f32_e32 v33, v85, v33
	v_add_f32_e32 v8, v8, v33
	v_add_f32_e32 v33, v9, v8
	v_pk_mul_f32 v[84:85], v[52:53], v[52:53]
	v_pk_mul_f32 v[8:9], v[54:55], v[54:55]
	v_add_f32_e32 v33, v84, v33
	v_add_f32_e32 v33, v85, v33
	v_add_f32_e32 v8, v8, v33
	v_add_f32_e32 v33, v9, v8
	ds_swizzle_b32 v84, v33 offset:swizzle(SWAP,16)
	v_pk_mul_f32 v[90:91], v[16:17], v[16:17]
	v_pk_mul_f32 v[88:89], v[18:19], v[18:19]
	s_waitcnt lgkmcnt(0)
	v_add_f32_e32 v85, v33, v84
	v_mul_f32_e32 v84, v49, v49
	v_fmac_f32_e32 v84, v48, v48
	v_fmac_f32_e32 v84, v50, v50
	v_fmac_f32_e32 v84, v51, v51
	v_fmac_f32_e32 v84, v44, v44
	v_fmac_f32_e32 v84, v45, v45
	v_fmac_f32_e32 v84, v46, v46
	v_fmac_f32_e32 v84, v47, v47
	v_fmac_f32_e32 v84, v40, v40
	v_fmac_f32_e32 v84, v41, v41
	v_fmac_f32_e32 v84, v42, v42
	v_fmac_f32_e32 v84, v43, v43
	v_fmac_f32_e32 v84, v36, v36
	v_fmac_f32_e32 v84, v37, v37
	v_fmac_f32_e32 v84, v38, v38
	v_fmac_f32_e32 v84, v39, v39
	v_fmac_f32_e32 v84, v24, v24
	v_fmac_f32_e32 v84, v25, v25
	v_fmac_f32_e32 v84, v26, v26
	v_fmac_f32_e32 v84, v27, v27
	v_fmac_f32_e32 v84, v20, v20
	v_fmac_f32_e32 v84, v21, v21
	v_fmac_f32_e32 v84, v22, v22
	v_fmac_f32_e32 v84, v23, v23
	v_add_f32_e32 v84, v90, v84
	v_add_f32_e32 v84, v91, v84
	v_add_f32_e32 v84, v88, v84
	v_add_f32_e32 v84, v89, v84
	v_pk_mul_f32 v[90:91], v[12:13], v[12:13]
	v_pk_mul_f32 v[88:89], v[14:15], v[14:15]
	v_add_f32_e32 v84, v90, v84
	v_add_f32_e32 v84, v91, v84
	v_add_f32_e32 v84, v88, v84
	v_add_f32_e32 v84, v89, v84
	ds_swizzle_b32 v86, v84 offset:swizzle(SWAP,16)
	v_mov_b32_e32 v87, v85
	s_nop 1
	v_permlane32_swap_b32_e32 v85, v87
	s_waitcnt lgkmcnt(0)
	v_add_f32_e32 v84, v84, v86
	v_mov_b32_e32 v86, v84
	s_nop 1
	v_permlane32_swap_b32_e32 v84, v86
	v_pk_add_f32 v[84:85], v[84:85], v[86:87]
	s_brev_b32 s0, 60
	v_mov_b32_e32 v34, 0x358637bd
	v_pk_fma_f32 v[84:85], v[84:85], s[0:1], v[34:35] op_sel_hi:[1,0,0]
	s_mov_b32 s2, 0x800000
	v_mul_f32_e32 v34, 0x4b800000, v85
	v_cmp_gt_f32_e32 vcc, s2, v85
	v_mul_f32_e32 v35, 0x4b800000, v84
	v_cmp_gt_f32_e64 s[0:1], s2, v84
	v_cndmask_b32_e32 v34, v85, v34, vcc
	v_rsq_f32_e32 v85, v34
	v_cndmask_b32_e64 v35, v84, v35, s[0:1]
	v_rsq_f32_e32 v84, v35
	v_mul_f32_e32 v92, 0x45800000, v85
	v_cndmask_b32_e32 v92, v85, v92, vcc
	v_mul_f32_e32 v94, 0x45800000, v84
	v_cndmask_b32_e64 v94, v84, v94, s[0:1]
	s_mov_b32 s87, s27
	s_mov_b32 m0, s90
	s_mov_b32 s42, 0x800000
	s_mov_b32 s5, 0
	s_waitcnt vmcnt(0)
; __device__ __forceinline__ unsigned cvtpk(float lo, float hi) { f32x2 v = {lo, hi}; bf16x2_t b = __builtin_convertvector(v, bf16x2_t); return __builtin_bit_cast(unsigned, b); }
; __device__ __forceinline__ float bflo(unsigned u) { return __uint_as_float(u << 16); }
; __device__ __forceinline__ float bfhi(unsigned u) { return __uint_as_float(u & 0xffff0000u); }
; __device__ __forceinline__ void ret_pair(LAS unsigned char* lds, const bf16_t* Z, bf16_t* MIX, int b, int h, int tA, int tB, const float* gain, int wid) {
;     ...
; #pragma unroll
;         for (int eb = 0; eb < 8; ++eb) {
;             const u32x2 gw = *(const u32x2*)(gp + 16 * eb);
;             const f32x4 gn = *(const f32x4*)(gain + 16 * eb + 4 * quadf);
;             u32x2 w; w.x = cvtpk(O[eb][0] * r * gn.x * bflo(gw.x), O[eb][1] * r * gn.y * bfhi(gw.x));
;             w.y = cvtpk(O[eb][2] * r * gn.z * bflo(gw.y), O[eb][3] * r * gn.w * bfhi(gw.y));
;             *(u32x2*)(op + 16 * eb) = w;
;         }
	ds_write_b64 v129, v[132:133]
	ds_read_b128 v[96:99], v128
	ds_read_b128 v[100:103], v128 offset:64
	ds_read_b128 v[104:107], v128 offset:128
	ds_read_b128 v[108:111], v128 offset:192
	ds_read_b128 v[112:115], v128 offset:256
	ds_read_b128 v[116:119], v128 offset:320
	ds_read_b128 v[120:123], v128 offset:384
	ds_read_b128 v[124:127], v128 offset:448
	v_permlane16_swap_b32_e32 v134, v136
	v_permlane16_swap_b32_e32 v135, v137
	v_permlane16_swap_b32_e32 v150, v152
	v_permlane16_swap_b32_e32 v151, v153
	v_permlane16_swap_b32_e32 v138, v140
	v_permlane16_swap_b32_e32 v139, v141
	v_permlane16_swap_b32_e32 v154, v156
	v_permlane16_swap_b32_e32 v155, v157
	v_permlane16_swap_b32_e32 v142, v144
	v_permlane16_swap_b32_e32 v143, v145
	v_permlane16_swap_b32_e32 v158, v160
	v_permlane16_swap_b32_e32 v159, v161
	v_permlane16_swap_b32_e32 v146, v148
	v_permlane16_swap_b32_e32 v147, v149
	v_permlane16_swap_b32_e32 v162, v164
	v_permlane16_swap_b32_e32 v163, v165
	s_waitcnt lgkmcnt(0)
	v_mbcnt_lo_u32_b32 v178, -1, 0
	v_mbcnt_hi_u32_b32 v178, -1, v178
	v_and_b32_e32 v178, 16, v178
	v_lshrrev_b32_e32 v179, 1, v178
	v_add_u32_e32 v178, v178, v179
	v_mov_b32_e32 v179, 0
	v_lshl_add_u64 v[174:175], v[166:167], 0, v[178:179]
	v_lshl_add_u64 v[176:177], v[168:169], 0, v[178:179]
	v_pk_mul_f32 v[80:81], v[80:81], v[92:93] op_sel_hi:[1,0]
	v_pk_mul_f32 v[82:83], v[82:83], v[92:93] op_sel_hi:[1,0]
	v_lshlrev_b32_e32 v28, 16, v134
	v_and_b32_e32 v29, 0xffff0000, v134
	v_lshlrev_b32_e32 v30, 16, v135
	v_and_b32_e32 v31, 0xffff0000, v135
	v_pk_mul_f32 v[80:81], v[96:97], v[80:81]
	v_pk_mul_f32 v[82:83], v[98:99], v[82:83]
	v_pk_mul_f32 v[80:81], v[80:81], v[28:29]
	v_pk_mul_f32 v[82:83], v[82:83], v[30:31]
	v_cvt_pk_bf16_f32 v80, v80, v81
	v_cvt_pk_bf16_f32 v81, v82, v83
	v_pk_mul_f32 v[76:77], v[76:77], v[92:93] op_sel_hi:[1,0]
	v_pk_mul_f32 v[78:79], v[78:79], v[92:93] op_sel_hi:[1,0]
	v_lshlrev_b32_e32 v170, 16, v136
	v_and_b32_e32 v171, 0xffff0000, v136
	v_lshlrev_b32_e32 v172, 16, v137
	v_and_b32_e32 v173, 0xffff0000, v137
	v_pk_mul_f32 v[76:77], v[100:101], v[76:77]
	v_pk_mul_f32 v[78:79], v[102:103], v[78:79]
	v_pk_mul_f32 v[76:77], v[76:77], v[170:171]
	v_pk_mul_f32 v[78:79], v[78:79], v[172:173]
	v_cvt_pk_bf16_f32 v82, v76, v77
	v_cvt_pk_bf16_f32 v83, v78, v79
	s_nop 1
	v_permlane16_swap_b32_e32 v80, v82
	v_permlane16_swap_b32_e32 v81, v83
	global_store_dwordx4 v[174:175], v[80:83], off
	v_pk_mul_f32 v[48:49], v[48:49], v[94:95] op_sel_hi:[1,0]
	v_pk_mul_f32 v[50:51], v[50:51], v[94:95] op_sel_hi:[1,0]
	v_lshlrev_b32_e32 v28, 16, v150
	v_and_b32_e32 v29, 0xffff0000, v150
	v_lshlrev_b32_e32 v30, 16, v151
	v_and_b32_e32 v31, 0xffff0000, v151
	v_pk_mul_f32 v[48:49], v[96:97], v[48:49]
	v_pk_mul_f32 v[50:51], v[98:99], v[50:51]
	v_pk_mul_f32 v[48:49], v[48:49], v[28:29]
	v_pk_mul_f32 v[50:51], v[50:51], v[30:31]
	v_cvt_pk_bf16_f32 v48, v48, v49
	v_cvt_pk_bf16_f32 v49, v50, v51
	v_pk_mul_f32 v[44:45], v[44:45], v[94:95] op_sel_hi:[1,0]
	v_pk_mul_f32 v[46:47], v[46:47], v[94:95] op_sel_hi:[1,0]
	v_lshlrev_b32_e32 v170, 16, v152
	v_and_b32_e32 v171, 0xffff0000, v152
	v_lshlrev_b32_e32 v172, 16, v153
	v_and_b32_e32 v173, 0xffff0000, v153
	v_pk_mul_f32 v[44:45], v[100:101], v[44:45]
	v_pk_mul_f32 v[46:47], v[102:103], v[46:47]
	v_pk_mul_f32 v[44:45], v[44:45], v[170:171]
	v_pk_mul_f32 v[46:47], v[46:47], v[172:173]
	v_cvt_pk_bf16_f32 v50, v44, v45
	v_cvt_pk_bf16_f32 v51, v46, v47
	s_nop 1
	v_permlane16_swap_b32_e32 v48, v50
	v_permlane16_swap_b32_e32 v49, v51
	global_store_dwordx4 v[176:177], v[48:51], off
	v_pk_mul_f32 v[72:73], v[72:73], v[92:93] op_sel_hi:[1,0]
	v_pk_mul_f32 v[74:75], v[74:75], v[92:93] op_sel_hi:[1,0]
	v_lshlrev_b32_e32 v28, 16, v138
	v_and_b32_e32 v29, 0xffff0000, v138
	v_lshlrev_b32_e32 v30, 16, v139
	v_and_b32_e32 v31, 0xffff0000, v139
	v_pk_mul_f32 v[72:73], v[104:105], v[72:73]
	v_pk_mul_f32 v[74:75], v[106:107], v[74:75]
	v_pk_mul_f32 v[72:73], v[72:73], v[28:29]
	v_pk_mul_f32 v[74:75], v[74:75], v[30:31]
	v_cvt_pk_bf16_f32 v72, v72, v73
	v_cvt_pk_bf16_f32 v73, v74, v75
	v_pk_mul_f32 v[68:69], v[68:69], v[92:93] op_sel_hi:[1,0]
	v_pk_mul_f32 v[70:71], v[70:71], v[92:93] op_sel_hi:[1,0]
	v_lshlrev_b32_e32 v170, 16, v140
	v_and_b32_e32 v171, 0xffff0000, v140
	v_lshlrev_b32_e32 v172, 16, v141
	v_and_b32_e32 v173, 0xffff0000, v141
	v_pk_mul_f32 v[68:69], v[108:109], v[68:69]
	v_pk_mul_f32 v[70:71], v[110:111], v[70:71]
	v_pk_mul_f32 v[68:69], v[68:69], v[170:171]
	v_pk_mul_f32 v[70:71], v[70:71], v[172:173]
	v_cvt_pk_bf16_f32 v74, v68, v69
	v_cvt_pk_bf16_f32 v75, v70, v71
	s_nop 1
	v_permlane16_swap_b32_e32 v72, v74
	v_permlane16_swap_b32_e32 v73, v75
	global_store_dwordx4 v[174:175], v[72:75], off offset:64
	v_pk_mul_f32 v[40:41], v[40:41], v[94:95] op_sel_hi:[1,0]
	v_pk_mul_f32 v[42:43], v[42:43], v[94:95] op_sel_hi:[1,0]
	v_lshlrev_b32_e32 v28, 16, v154
	v_and_b32_e32 v29, 0xffff0000, v154
	v_lshlrev_b32_e32 v30, 16, v155
	v_and_b32_e32 v31, 0xffff0000, v155
	v_pk_mul_f32 v[40:41], v[104:105], v[40:41]
	v_pk_mul_f32 v[42:43], v[106:107], v[42:43]
	v_pk_mul_f32 v[40:41], v[40:41], v[28:29]
	v_pk_mul_f32 v[42:43], v[42:43], v[30:31]
	v_cvt_pk_bf16_f32 v40, v40, v41
	v_cvt_pk_bf16_f32 v41, v42, v43
	v_pk_mul_f32 v[36:37], v[36:37], v[94:95] op_sel_hi:[1,0]
	v_pk_mul_f32 v[38:39], v[38:39], v[94:95] op_sel_hi:[1,0]
	v_lshlrev_b32_e32 v170, 16, v156
	v_and_b32_e32 v171, 0xffff0000, v156
	v_lshlrev_b32_e32 v172, 16, v157
	v_and_b32_e32 v173, 0xffff0000, v157
	v_pk_mul_f32 v[36:37], v[108:109], v[36:37]
	v_pk_mul_f32 v[38:39], v[110:111], v[38:39]
	v_pk_mul_f32 v[36:37], v[36:37], v[170:171]
	v_pk_mul_f32 v[38:39], v[38:39], v[172:173]
; __device__ __forceinline__ unsigned cvtpk(float lo, float hi) { f32x2 v = {lo, hi}; bf16x2_t b = __builtin_convertvector(v, bf16x2_t); return __builtin_bit_cast(unsigned, b); }
; __device__ __forceinline__ float bflo(unsigned u) { return __uint_as_float(u << 16); }
; __device__ __forceinline__ float bfhi(unsigned u) { return __uint_as_float(u & 0xffff0000u); }
; __device__ __forceinline__ void ret_pair(LAS unsigned char* lds, const bf16_t* Z, bf16_t* MIX, int b, int h, int tA, int tB, const float* gain, int wid) {
;     ...
; #pragma unroll
;         for (int eb = 0; eb < 8; ++eb) {
;             const u32x2 gw = *(const u32x2*)(gp + 16 * eb);
;             const f32x4 gn = *(const f32x4*)(gain + 16 * eb + 4 * quadf);
;             u32x2 w; w.x = cvtpk(O[eb][0] * r * gn.x * bflo(gw.x), O[eb][1] * r * gn.y * bfhi(gw.x));
;             w.y = cvtpk(O[eb][2] * r * gn.z * bflo(gw.y), O[eb][3] * r * gn.w * bfhi(gw.y));
;             *(u32x2*)(op + 16 * eb) = w;
;         }
; __global__ void __launch_bounds__(NWAVES * 64, 2) fwd(Args args) {
;     ...
;         for (int pi = vcu; pi < 256; pi += G) {
;             const int bh = pi >> 3, tp = pi & 7, b = bh >> 3, h = bh & 7;
;             attn_item<true>(lds, Z, MIX, b, h, 15 - tp, lam, shift, subln, 0, wid, 0);
;             ret_pair(lds, Z, MIX, b, h, 15 - tp, tp, ret_gn + 128 * h, wid);
;             attn_item<true>(lds, Z, MIX, b, h, tp, lam, shift, subln, 0, wid, 0);
;         }
	v_cvt_pk_bf16_f32 v42, v36, v37
	v_cvt_pk_bf16_f32 v43, v38, v39
	s_nop 1
	v_permlane16_swap_b32_e32 v40, v42
	v_permlane16_swap_b32_e32 v41, v43
	global_store_dwordx4 v[176:177], v[40:43], off offset:64
	v_pk_mul_f32 v[64:65], v[64:65], v[92:93] op_sel_hi:[1,0]
	v_pk_mul_f32 v[66:67], v[66:67], v[92:93] op_sel_hi:[1,0]
	v_lshlrev_b32_e32 v28, 16, v142
	v_and_b32_e32 v29, 0xffff0000, v142
	v_lshlrev_b32_e32 v30, 16, v143
	v_and_b32_e32 v31, 0xffff0000, v143
	v_pk_mul_f32 v[64:65], v[112:113], v[64:65]
	v_pk_mul_f32 v[66:67], v[114:115], v[66:67]
	v_pk_mul_f32 v[64:65], v[64:65], v[28:29]
	v_pk_mul_f32 v[66:67], v[66:67], v[30:31]
	v_cvt_pk_bf16_f32 v64, v64, v65
	v_cvt_pk_bf16_f32 v65, v66, v67
	v_pk_mul_f32 v[60:61], v[60:61], v[92:93] op_sel_hi:[1,0]
	v_pk_mul_f32 v[62:63], v[62:63], v[92:93] op_sel_hi:[1,0]
	v_lshlrev_b32_e32 v170, 16, v144
	v_and_b32_e32 v171, 0xffff0000, v144
	v_lshlrev_b32_e32 v172, 16, v145
	v_and_b32_e32 v173, 0xffff0000, v145
	v_pk_mul_f32 v[60:61], v[116:117], v[60:61]
	v_pk_mul_f32 v[62:63], v[118:119], v[62:63]
	v_pk_mul_f32 v[60:61], v[60:61], v[170:171]
	v_pk_mul_f32 v[62:63], v[62:63], v[172:173]
	v_cvt_pk_bf16_f32 v66, v60, v61
	v_cvt_pk_bf16_f32 v67, v62, v63
	s_nop 1
	v_permlane16_swap_b32_e32 v64, v66
	v_permlane16_swap_b32_e32 v65, v67
	global_store_dwordx4 v[174:175], v[64:67], off offset:128
	v_pk_mul_f32 v[24:25], v[24:25], v[94:95] op_sel_hi:[1,0]
	v_pk_mul_f32 v[26:27], v[26:27], v[94:95] op_sel_hi:[1,0]
	v_lshlrev_b32_e32 v28, 16, v158
	v_and_b32_e32 v29, 0xffff0000, v158
	v_lshlrev_b32_e32 v30, 16, v159
	v_and_b32_e32 v31, 0xffff0000, v159
	v_pk_mul_f32 v[24:25], v[112:113], v[24:25]
	v_pk_mul_f32 v[26:27], v[114:115], v[26:27]
	v_pk_mul_f32 v[24:25], v[24:25], v[28:29]
	v_pk_mul_f32 v[26:27], v[26:27], v[30:31]
	v_cvt_pk_bf16_f32 v24, v24, v25
	v_cvt_pk_bf16_f32 v25, v26, v27
	v_pk_mul_f32 v[20:21], v[20:21], v[94:95] op_sel_hi:[1,0]
	v_pk_mul_f32 v[22:23], v[22:23], v[94:95] op_sel_hi:[1,0]
	v_lshlrev_b32_e32 v170, 16, v160
	v_and_b32_e32 v171, 0xffff0000, v160
	v_lshlrev_b32_e32 v172, 16, v161
	v_and_b32_e32 v173, 0xffff0000, v161
	v_pk_mul_f32 v[20:21], v[116:117], v[20:21]
	v_pk_mul_f32 v[22:23], v[118:119], v[22:23]
	v_pk_mul_f32 v[20:21], v[20:21], v[170:171]
	v_pk_mul_f32 v[22:23], v[22:23], v[172:173]
	v_cvt_pk_bf16_f32 v26, v20, v21
	v_cvt_pk_bf16_f32 v27, v22, v23
	s_nop 1
	v_permlane16_swap_b32_e32 v24, v26
	v_permlane16_swap_b32_e32 v25, v27
	global_store_dwordx4 v[176:177], v[24:27], off offset:128
	v_pk_mul_f32 v[56:57], v[56:57], v[92:93] op_sel_hi:[1,0]
	v_pk_mul_f32 v[58:59], v[58:59], v[92:93] op_sel_hi:[1,0]
	v_lshlrev_b32_e32 v28, 16, v146
	v_and_b32_e32 v29, 0xffff0000, v146
	v_lshlrev_b32_e32 v30, 16, v147
	v_and_b32_e32 v31, 0xffff0000, v147
	v_pk_mul_f32 v[56:57], v[120:121], v[56:57]
	v_pk_mul_f32 v[58:59], v[122:123], v[58:59]
	v_pk_mul_f32 v[56:57], v[56:57], v[28:29]
	v_pk_mul_f32 v[58:59], v[58:59], v[30:31]
	v_cvt_pk_bf16_f32 v56, v56, v57
	v_cvt_pk_bf16_f32 v57, v58, v59
	v_pk_mul_f32 v[52:53], v[52:53], v[92:93] op_sel_hi:[1,0]
	v_pk_mul_f32 v[54:55], v[54:55], v[92:93] op_sel_hi:[1,0]
	v_lshlrev_b32_e32 v170, 16, v148
	v_and_b32_e32 v171, 0xffff0000, v148
	v_lshlrev_b32_e32 v172, 16, v149
	v_and_b32_e32 v173, 0xffff0000, v149
	v_pk_mul_f32 v[52:53], v[124:125], v[52:53]
	v_pk_mul_f32 v[54:55], v[126:127], v[54:55]
	v_pk_mul_f32 v[52:53], v[52:53], v[170:171]
	v_pk_mul_f32 v[54:55], v[54:55], v[172:173]
	v_cvt_pk_bf16_f32 v58, v52, v53
	v_cvt_pk_bf16_f32 v59, v54, v55
	s_nop 1
	v_permlane16_swap_b32_e32 v56, v58
	v_permlane16_swap_b32_e32 v57, v59
	global_store_dwordx4 v[174:175], v[56:59], off offset:192
	v_pk_mul_f32 v[16:17], v[16:17], v[94:95] op_sel_hi:[1,0]
	v_pk_mul_f32 v[18:19], v[18:19], v[94:95] op_sel_hi:[1,0]
	v_lshlrev_b32_e32 v28, 16, v162
	v_and_b32_e32 v29, 0xffff0000, v162
	v_lshlrev_b32_e32 v30, 16, v163
	v_and_b32_e32 v31, 0xffff0000, v163
	v_pk_mul_f32 v[16:17], v[120:121], v[16:17]
	v_pk_mul_f32 v[18:19], v[122:123], v[18:19]
	v_pk_mul_f32 v[16:17], v[16:17], v[28:29]
	v_pk_mul_f32 v[18:19], v[18:19], v[30:31]
	v_cvt_pk_bf16_f32 v16, v16, v17
	v_cvt_pk_bf16_f32 v17, v18, v19
	v_pk_mul_f32 v[12:13], v[12:13], v[94:95] op_sel_hi:[1,0]
	v_pk_mul_f32 v[14:15], v[14:15], v[94:95] op_sel_hi:[1,0]
	v_lshlrev_b32_e32 v170, 16, v164
	v_and_b32_e32 v171, 0xffff0000, v164
	v_lshlrev_b32_e32 v172, 16, v165
	v_and_b32_e32 v173, 0xffff0000, v165
	v_pk_mul_f32 v[12:13], v[124:125], v[12:13]
	v_pk_mul_f32 v[14:15], v[126:127], v[14:15]
	v_pk_mul_f32 v[12:13], v[12:13], v[170:171]
	v_pk_mul_f32 v[14:15], v[14:15], v[172:173]
	v_cvt_pk_bf16_f32 v18, v12, v13
	v_cvt_pk_bf16_f32 v19, v14, v15
	s_nop 1
	v_permlane16_swap_b32_e32 v16, v18
	v_permlane16_swap_b32_e32 v17, v19
	global_store_dwordx4 v[176:177], v[16:19], off offset:192
	s_nop 1
	v_readlane_b32 s17, v254, 44
	v_readlane_b32 s38, v254, 45
	v_readlane_b32 s39, v254, 46
	v_readlane_b32 s18, v254, 47
	v_readlane_b32 s40, v254, 48
	v_readlane_b32 s41, v254, 49
	v_readlane_b32 s43, v254, 50
	v_readlane_b32 s28, v254, 36
	v_readlane_b32 s30, v254, 37
	v_readlane_b32 s31, v254, 38
	v_readlane_b32 s88, v254, 39
	v_readlane_b32 s89, v254, 40
	v_readlane_b32 s29, v254, 41
	v_readlane_b32 s34, v254, 42
	v_readlane_b32 s35, v254, 43
	v_readlane_b32 s66, v254, 33
	v_readlane_b32 s84, v254, 34
	v_readlane_b32 s85, v254, 35
	v_readlane_b32 s78, v254, 32
	s_mov_b32 s27, 0
	s_movk_i32 s36, 0x3800
	s_mov_b64 s[14:15], 0x1800
	s_movk_i32 s16, 0x1000
	s_movk_i32 s37, 0x1c00
	s_mov_b64 s[96:97], 0x80
	s_movk_i32 s67, 0xe0
	s_movk_i32 s73, 0x60
	s_movk_i32 s74, 0x80
	s_movk_i32 s75, 0xa0
	s_movk_i32 s79, 0xc0
	s_mov_b64 s[92:93], 0x3000
	s_mov_b32 s42, 0x800000
	v_readlane_b32 s44, v255, 2
	v_readlane_b32 s2, v254, 51
	s_mov_b32 s98, 1
	s_mov_b32 s99, 0x01234567
	s_branch .LBB0_565
